# combo6 with the static GEMM priority raise on waves 0-3 instead of waves 4-7 (per-half A/B)
# speedup vs baseline: 1.0020x; 1.0020x over previous
.LBB0_218:
	s_ashr_i32 s27, s26, 31
	s_lshl_b64 s[4:5], s[26:27], 20
	s_add_u32 s30, s48, s4
	s_addc_u32 s31, s49, s5
	s_and_b64 s[4:5], s[36:37], exec
	s_cselect_b32 s4, s31, s43
	s_cselect_b32 s5, s30, s42
	s_ashr_i32 s23, s22, 31
	s_lshl_b64 s[38:39], s[22:23], 20
	s_add_u32 s38, s24, s38
	s_addc_u32 s39, s50, s39
	s_and_b64 s[46:47], s[36:37], exec
	s_cselect_b32 s23, s39, s35
	s_cselect_b32 s27, s38, s34
	s_add_u32 s61, s34, 0x100
	s_addc_u32 s62, s35, 0
	s_add_u32 s42, s42, 0x80080
	v_mov_b32_e32 v0, 0
	s_addc_u32 s43, s43, 0
	s_mov_b32 s63, -2
	v_mov_b32_e32 v1, v0
	v_mov_b32_e32 v2, v0
	v_mov_b32_e32 v3, v0
	v_mov_b32_e32 v8, v0
	v_mov_b32_e32 v9, v0
	v_mov_b32_e32 v10, v0
	v_mov_b32_e32 v11, v0
	v_mov_b32_e32 v18, v0
	v_mov_b32_e32 v19, v0
	v_mov_b32_e32 v20, v0
	v_mov_b32_e32 v21, v0
	v_mov_b32_e32 v26, v0
	v_mov_b32_e32 v27, v0
	v_mov_b32_e32 v28, v0
	v_mov_b32_e32 v29, v0
	v_mov_b32_e32 v34, v0
	v_mov_b32_e32 v35, v0
	v_mov_b32_e32 v36, v0
	v_mov_b32_e32 v37, v0
	v_mov_b32_e32 v42, v0
	v_mov_b32_e32 v43, v0
	v_mov_b32_e32 v44, v0
	v_mov_b32_e32 v45, v0
	v_mov_b32_e32 v50, v0
	v_mov_b32_e32 v51, v0
	v_mov_b32_e32 v52, v0
	v_mov_b32_e32 v53, v0
	v_mov_b32_e32 v58, v0
	v_mov_b32_e32 v59, v0
	v_mov_b32_e32 v60, v0
	v_mov_b32_e32 v61, v0
	v_mov_b32_e32 v4, v0
	v_mov_b32_e32 v5, v0
	v_mov_b32_e32 v6, v0
	v_mov_b32_e32 v7, v0
	v_mov_b32_e32 v12, v0
	v_mov_b32_e32 v13, v0
	v_mov_b32_e32 v14, v0
	v_mov_b32_e32 v15, v0
	v_mov_b32_e32 v22, v0
	v_mov_b32_e32 v23, v0
	v_mov_b32_e32 v24, v0
	v_mov_b32_e32 v25, v0
	v_mov_b32_e32 v30, v0
	v_mov_b32_e32 v31, v0
	v_mov_b32_e32 v32, v0
	v_mov_b32_e32 v33, v0
	v_mov_b32_e32 v38, v0
	v_mov_b32_e32 v39, v0
	v_mov_b32_e32 v40, v0
	v_mov_b32_e32 v41, v0
	v_mov_b32_e32 v46, v0
	v_mov_b32_e32 v47, v0
	v_mov_b32_e32 v48, v0
	v_mov_b32_e32 v49, v0
	v_mov_b32_e32 v54, v0
	v_mov_b32_e32 v55, v0
	v_mov_b32_e32 v56, v0
	v_mov_b32_e32 v57, v0
	v_mov_b32_e32 v62, v0
	v_mov_b32_e32 v63, v0
	v_mov_b32_e32 v64, v0
	v_mov_b32_e32 v65, v0
	v_mov_b32_e32 v66, v0
	v_mov_b32_e32 v67, v0
	v_mov_b32_e32 v68, v0
	v_mov_b32_e32 v69, v0
	v_mov_b32_e32 v74, v0
	v_mov_b32_e32 v75, v0
	v_mov_b32_e32 v76, v0
	v_mov_b32_e32 v77, v0
	v_mov_b32_e32 v82, v0
	v_mov_b32_e32 v83, v0
	v_mov_b32_e32 v84, v0
	v_mov_b32_e32 v85, v0
	v_mov_b32_e32 v90, v0
	v_mov_b32_e32 v91, v0
	v_mov_b32_e32 v92, v0
	v_mov_b32_e32 v93, v0
	v_mov_b32_e32 v98, v0
	v_mov_b32_e32 v99, v0
	v_mov_b32_e32 v100, v0
	v_mov_b32_e32 v101, v0
	v_mov_b32_e32 v106, v0
	v_mov_b32_e32 v107, v0
	v_mov_b32_e32 v108, v0
	v_mov_b32_e32 v109, v0
	v_mov_b32_e32 v114, v0
	v_mov_b32_e32 v115, v0
	v_mov_b32_e32 v116, v0
	v_mov_b32_e32 v117, v0
	v_mov_b32_e32 v122, v0
	v_mov_b32_e32 v123, v0
	v_mov_b32_e32 v124, v0
	v_mov_b32_e32 v125, v0
	v_mov_b32_e32 v70, v0
	v_mov_b32_e32 v71, v0
	v_mov_b32_e32 v72, v0
	v_mov_b32_e32 v73, v0
	v_mov_b32_e32 v78, v0
	v_mov_b32_e32 v79, v0
	v_mov_b32_e32 v80, v0
	v_mov_b32_e32 v81, v0
	v_mov_b32_e32 v86, v0
	v_mov_b32_e32 v87, v0
	v_mov_b32_e32 v88, v0
	v_mov_b32_e32 v89, v0
	v_mov_b32_e32 v94, v0
	v_mov_b32_e32 v95, v0
	v_mov_b32_e32 v96, v0
	v_mov_b32_e32 v97, v0
	v_mov_b32_e32 v102, v0
	v_mov_b32_e32 v103, v0
	v_mov_b32_e32 v104, v0
	v_mov_b32_e32 v105, v0
	v_mov_b32_e32 v110, v0
	v_mov_b32_e32 v111, v0
	v_mov_b32_e32 v112, v0
	v_mov_b32_e32 v113, v0
	v_mov_b32_e32 v118, v0
	v_mov_b32_e32 v119, v0
	v_mov_b32_e32 v120, v0
	v_mov_b32_e32 v121, v0
	v_mov_b32_e32 v126, v0
	v_mov_b32_e32 v127, v0
	v_mov_b32_e32 v128, v0
	v_mov_b32_e32 v129, v0
	s_and_b64 vcc, exec, s[20:21]
	s_cbranch_vccz .Lprio_skip_0
	s_setprio 1

.LBB0_299:
	s_add_u32 s4, s34, 0x100
	v_mov_b32_e32 v0, 0
	s_addc_u32 s5, s35, 0
	s_mov_b32 s63, -2
	v_mov_b32_e32 v1, v0
	v_mov_b32_e32 v2, v0
	v_mov_b32_e32 v3, v0
	v_mov_b32_e32 v4, v0
	v_mov_b32_e32 v5, v0
	v_mov_b32_e32 v6, v0
	v_mov_b32_e32 v7, v0
	v_mov_b32_e32 v8, v0
	v_mov_b32_e32 v9, v0
	v_mov_b32_e32 v10, v0
	v_mov_b32_e32 v11, v0
	v_mov_b32_e32 v12, v0
	v_mov_b32_e32 v13, v0
	v_mov_b32_e32 v14, v0
	v_mov_b32_e32 v15, v0
	v_mov_b32_e32 v18, v0
	v_mov_b32_e32 v19, v0
	v_mov_b32_e32 v20, v0
	v_mov_b32_e32 v21, v0
	v_mov_b32_e32 v22, v0
	v_mov_b32_e32 v23, v0
	v_mov_b32_e32 v24, v0
	v_mov_b32_e32 v25, v0
	v_mov_b32_e32 v26, v0
	v_mov_b32_e32 v27, v0
	v_mov_b32_e32 v28, v0
	v_mov_b32_e32 v29, v0
	v_mov_b32_e32 v30, v0
	v_mov_b32_e32 v31, v0
	v_mov_b32_e32 v32, v0
	v_mov_b32_e32 v33, v0
	v_mov_b32_e32 v66, v0
	v_mov_b32_e32 v67, v0
	v_mov_b32_e32 v68, v0
	v_mov_b32_e32 v69, v0
	v_mov_b32_e32 v70, v0
	v_mov_b32_e32 v71, v0
	v_mov_b32_e32 v72, v0
	v_mov_b32_e32 v73, v0
	v_mov_b32_e32 v74, v0
	v_mov_b32_e32 v75, v0
	v_mov_b32_e32 v76, v0
	v_mov_b32_e32 v77, v0
	v_mov_b32_e32 v78, v0
	v_mov_b32_e32 v79, v0
	v_mov_b32_e32 v80, v0
	v_mov_b32_e32 v81, v0
	v_mov_b32_e32 v82, v0
	v_mov_b32_e32 v83, v0
	v_mov_b32_e32 v84, v0
	v_mov_b32_e32 v85, v0
	v_mov_b32_e32 v86, v0
	v_mov_b32_e32 v87, v0
	v_mov_b32_e32 v88, v0
	v_mov_b32_e32 v89, v0
	v_mov_b32_e32 v90, v0
	v_mov_b32_e32 v91, v0
	v_mov_b32_e32 v92, v0
	v_mov_b32_e32 v93, v0
	v_mov_b32_e32 v94, v0
	v_mov_b32_e32 v95, v0
	v_mov_b32_e32 v96, v0
	v_mov_b32_e32 v97, v0
	v_mov_b32_e32 v34, v0
	v_mov_b32_e32 v35, v0
	v_mov_b32_e32 v36, v0
	v_mov_b32_e32 v37, v0
	v_mov_b32_e32 v38, v0
	v_mov_b32_e32 v39, v0
	v_mov_b32_e32 v40, v0
	v_mov_b32_e32 v41, v0
	v_mov_b32_e32 v42, v0
	v_mov_b32_e32 v43, v0
	v_mov_b32_e32 v44, v0
	v_mov_b32_e32 v45, v0
	v_mov_b32_e32 v46, v0
	v_mov_b32_e32 v47, v0
	v_mov_b32_e32 v48, v0
	v_mov_b32_e32 v49, v0
	v_mov_b32_e32 v50, v0
	v_mov_b32_e32 v51, v0
	v_mov_b32_e32 v52, v0
	v_mov_b32_e32 v53, v0
	v_mov_b32_e32 v54, v0
	v_mov_b32_e32 v55, v0
	v_mov_b32_e32 v56, v0
	v_mov_b32_e32 v57, v0
	v_mov_b32_e32 v58, v0
	v_mov_b32_e32 v59, v0
	v_mov_b32_e32 v60, v0
	v_mov_b32_e32 v61, v0
	v_mov_b32_e32 v62, v0
	v_mov_b32_e32 v63, v0
	v_mov_b32_e32 v64, v0
	v_mov_b32_e32 v65, v0
	v_mov_b32_e32 v98, v0
	v_mov_b32_e32 v99, v0
	v_mov_b32_e32 v100, v0
	v_mov_b32_e32 v101, v0
	v_mov_b32_e32 v102, v0
	v_mov_b32_e32 v103, v0
	v_mov_b32_e32 v104, v0
	v_mov_b32_e32 v105, v0
	v_mov_b32_e32 v106, v0
	v_mov_b32_e32 v107, v0
	v_mov_b32_e32 v108, v0
	v_mov_b32_e32 v109, v0
	v_mov_b32_e32 v110, v0
	v_mov_b32_e32 v111, v0
	v_mov_b32_e32 v112, v0
	v_mov_b32_e32 v113, v0
	v_mov_b32_e32 v114, v0
	v_mov_b32_e32 v115, v0
	v_mov_b32_e32 v116, v0
	v_mov_b32_e32 v117, v0
	v_mov_b32_e32 v118, v0
	v_mov_b32_e32 v119, v0
	v_mov_b32_e32 v120, v0
	v_mov_b32_e32 v121, v0
	v_mov_b32_e32 v122, v0
	v_mov_b32_e32 v123, v0
	v_mov_b32_e32 v124, v0
	v_mov_b32_e32 v125, v0
	v_mov_b32_e32 v126, v0
	v_mov_b32_e32 v127, v0
	v_mov_b32_e32 v128, v0
	v_mov_b32_e32 v129, v0
	s_and_b64 vcc, exec, s[20:21]
	s_cbranch_vccz .Lprio_skip_1
	s_setprio 1

.LBB0_429:
	s_ashr_i32 s27, s26, 31
	s_lshl_b64 s[4:5], s[26:27], 20
	s_add_u32 s38, s48, s4
	s_addc_u32 s39, s49, s5
	s_and_b64 s[4:5], s[36:37], exec
	s_cselect_b32 s4, s39, s43
	s_cselect_b32 s5, s38, s42
	s_ashr_i32 s23, s22, 31
	s_lshl_b64 s[40:41], s[22:23], 20
	s_add_u32 s40, s24, s40
	s_addc_u32 s41, s50, s41
	s_and_b64 s[46:47], s[36:37], exec
	s_cselect_b32 s23, s41, s35
	s_cselect_b32 s27, s40, s34
	s_add_u32 s61, s34, 0x100
	s_addc_u32 s62, s35, 0
	s_add_u32 s42, s42, 0x80080
	v_mov_b32_e32 v0, 0
	s_addc_u32 s43, s43, 0
	s_mov_b32 s63, -2
	v_mov_b32_e32 v1, v0
	v_mov_b32_e32 v2, v0
	v_mov_b32_e32 v3, v0
	v_mov_b32_e32 v4, v0
	v_mov_b32_e32 v5, v0
	v_mov_b32_e32 v6, v0
	v_mov_b32_e32 v7, v0
	v_mov_b32_e32 v8, v0
	v_mov_b32_e32 v9, v0
	v_mov_b32_e32 v10, v0
	v_mov_b32_e32 v11, v0
	v_mov_b32_e32 v18, v0
	v_mov_b32_e32 v19, v0
	v_mov_b32_e32 v20, v0
	v_mov_b32_e32 v21, v0
	v_mov_b32_e32 v26, v0
	v_mov_b32_e32 v27, v0
	v_mov_b32_e32 v28, v0
	v_mov_b32_e32 v29, v0
	v_mov_b32_e32 v34, v0
	v_mov_b32_e32 v35, v0
	v_mov_b32_e32 v36, v0
	v_mov_b32_e32 v37, v0
	v_mov_b32_e32 v42, v0
	v_mov_b32_e32 v43, v0
	v_mov_b32_e32 v44, v0
	v_mov_b32_e32 v45, v0
	v_mov_b32_e32 v50, v0
	v_mov_b32_e32 v51, v0
	v_mov_b32_e32 v52, v0
	v_mov_b32_e32 v53, v0
	v_mov_b32_e32 v12, v0
	v_mov_b32_e32 v13, v0
	v_mov_b32_e32 v14, v0
	v_mov_b32_e32 v15, v0
	v_mov_b32_e32 v22, v0
	v_mov_b32_e32 v23, v0
	v_mov_b32_e32 v24, v0
	v_mov_b32_e32 v25, v0
	v_mov_b32_e32 v30, v0
	v_mov_b32_e32 v31, v0
	v_mov_b32_e32 v32, v0
	v_mov_b32_e32 v33, v0
	v_mov_b32_e32 v38, v0
	v_mov_b32_e32 v39, v0
	v_mov_b32_e32 v40, v0
	v_mov_b32_e32 v41, v0
	v_mov_b32_e32 v46, v0
	v_mov_b32_e32 v47, v0
	v_mov_b32_e32 v48, v0
	v_mov_b32_e32 v49, v0
	v_mov_b32_e32 v54, v0
	v_mov_b32_e32 v55, v0
	v_mov_b32_e32 v56, v0
	v_mov_b32_e32 v57, v0
	v_mov_b32_e32 v58, v0
	v_mov_b32_e32 v59, v0
	v_mov_b32_e32 v60, v0
	v_mov_b32_e32 v61, v0
	v_mov_b32_e32 v62, v0
	v_mov_b32_e32 v63, v0
	v_mov_b32_e32 v64, v0
	v_mov_b32_e32 v65, v0
	v_mov_b32_e32 v66, v0
	v_mov_b32_e32 v67, v0
	v_mov_b32_e32 v68, v0
	v_mov_b32_e32 v69, v0
	v_mov_b32_e32 v70, v0
	v_mov_b32_e32 v71, v0
	v_mov_b32_e32 v72, v0
	v_mov_b32_e32 v73, v0
	v_mov_b32_e32 v74, v0
	v_mov_b32_e32 v75, v0
	v_mov_b32_e32 v76, v0
	v_mov_b32_e32 v77, v0
	v_mov_b32_e32 v82, v0
	v_mov_b32_e32 v83, v0
	v_mov_b32_e32 v84, v0
	v_mov_b32_e32 v85, v0
	v_mov_b32_e32 v90, v0
	v_mov_b32_e32 v91, v0
	v_mov_b32_e32 v92, v0
	v_mov_b32_e32 v93, v0
	v_mov_b32_e32 v98, v0
	v_mov_b32_e32 v99, v0
	v_mov_b32_e32 v100, v0
	v_mov_b32_e32 v101, v0
	v_mov_b32_e32 v106, v0
	v_mov_b32_e32 v107, v0
	v_mov_b32_e32 v108, v0
	v_mov_b32_e32 v109, v0
	v_mov_b32_e32 v114, v0
	v_mov_b32_e32 v115, v0
	v_mov_b32_e32 v116, v0
	v_mov_b32_e32 v117, v0
	v_mov_b32_e32 v78, v0
	v_mov_b32_e32 v79, v0
	v_mov_b32_e32 v80, v0
	v_mov_b32_e32 v81, v0
	v_mov_b32_e32 v86, v0
	v_mov_b32_e32 v87, v0
	v_mov_b32_e32 v88, v0
	v_mov_b32_e32 v89, v0
	v_mov_b32_e32 v94, v0
	v_mov_b32_e32 v95, v0
	v_mov_b32_e32 v96, v0
	v_mov_b32_e32 v97, v0
	v_mov_b32_e32 v102, v0
	v_mov_b32_e32 v103, v0
	v_mov_b32_e32 v104, v0
	v_mov_b32_e32 v105, v0
	v_mov_b32_e32 v110, v0
	v_mov_b32_e32 v111, v0
	v_mov_b32_e32 v112, v0
	v_mov_b32_e32 v113, v0
	v_mov_b32_e32 v118, v0
	v_mov_b32_e32 v119, v0
	v_mov_b32_e32 v120, v0
	v_mov_b32_e32 v121, v0
	v_mov_b32_e32 v122, v0
	v_mov_b32_e32 v123, v0
	v_mov_b32_e32 v124, v0
	v_mov_b32_e32 v125, v0
	v_mov_b32_e32 v126, v0
	v_mov_b32_e32 v127, v0
	v_mov_b32_e32 v128, v0
	v_mov_b32_e32 v129, v0
	s_and_b64 vcc, exec, s[20:21]
	s_cbranch_vccz .Lprio_skip_2
	s_setprio 1

.LBB0_1622:
	s_ashr_i32 s27, s26, 31
	s_lshl_b64 s[4:5], s[26:27], 20
	s_add_u32 s30, s46, s4
	s_addc_u32 s31, s47, s5
	s_and_b64 s[4:5], s[36:37], exec
	s_cselect_b32 s4, s31, s43
	s_cselect_b32 s5, s30, s42
	s_ashr_i32 s23, s22, 31
	s_lshl_b64 s[38:39], s[22:23], 20
	s_add_u32 s38, s48, s38
	s_addc_u32 s39, s49, s39
	s_and_b64 s[44:45], s[36:37], exec
	s_cselect_b32 s23, s39, s35
	s_cselect_b32 s27, s38, s34
	s_add_u32 s61, s34, 0x100
	s_addc_u32 s62, s35, 0
	s_add_u32 s42, s42, 0x80080
	v_mov_b32_e32 v0, 0
	s_addc_u32 s43, s43, 0
	s_mov_b32 s63, -2
	v_mov_b32_e32 v1, v0
	v_mov_b32_e32 v2, v0
	v_mov_b32_e32 v3, v0
	v_mov_b32_e32 v4, v0
	v_mov_b32_e32 v5, v0
	v_mov_b32_e32 v6, v0
	v_mov_b32_e32 v7, v0
	v_mov_b32_e32 v8, v0
	v_mov_b32_e32 v9, v0
	v_mov_b32_e32 v10, v0
	v_mov_b32_e32 v11, v0
	v_mov_b32_e32 v12, v0
	v_mov_b32_e32 v13, v0
	v_mov_b32_e32 v14, v0
	v_mov_b32_e32 v15, v0
	v_mov_b32_e32 v18, v0
	v_mov_b32_e32 v19, v0
	v_mov_b32_e32 v20, v0
	v_mov_b32_e32 v21, v0
	v_mov_b32_e32 v22, v0
	v_mov_b32_e32 v23, v0
	v_mov_b32_e32 v24, v0
	v_mov_b32_e32 v25, v0
	v_mov_b32_e32 v26, v0
	v_mov_b32_e32 v27, v0
	v_mov_b32_e32 v28, v0
	v_mov_b32_e32 v29, v0
	v_mov_b32_e32 v30, v0
	v_mov_b32_e32 v31, v0
	v_mov_b32_e32 v32, v0
	v_mov_b32_e32 v33, v0
	v_mov_b32_e32 v58, v0
	v_mov_b32_e32 v59, v0
	v_mov_b32_e32 v60, v0
	v_mov_b32_e32 v61, v0
	v_mov_b32_e32 v66, v0
	v_mov_b32_e32 v67, v0
	v_mov_b32_e32 v68, v0
	v_mov_b32_e32 v69, v0
	v_mov_b32_e32 v74, v0
	v_mov_b32_e32 v75, v0
	v_mov_b32_e32 v76, v0
	v_mov_b32_e32 v77, v0
	v_mov_b32_e32 v78, v0
	v_mov_b32_e32 v79, v0
	v_mov_b32_e32 v80, v0
	v_mov_b32_e32 v81, v0
	v_mov_b32_e32 v82, v0
	v_mov_b32_e32 v83, v0
	v_mov_b32_e32 v84, v0
	v_mov_b32_e32 v85, v0
	v_mov_b32_e32 v86, v0
	v_mov_b32_e32 v87, v0
	v_mov_b32_e32 v88, v0
	v_mov_b32_e32 v89, v0
	v_mov_b32_e32 v90, v0
	v_mov_b32_e32 v91, v0
	v_mov_b32_e32 v92, v0
	v_mov_b32_e32 v93, v0
	v_mov_b32_e32 v94, v0
	v_mov_b32_e32 v95, v0
	v_mov_b32_e32 v96, v0
	v_mov_b32_e32 v97, v0
	v_mov_b32_e32 v34, v0
	v_mov_b32_e32 v35, v0
	v_mov_b32_e32 v36, v0
	v_mov_b32_e32 v37, v0
	v_mov_b32_e32 v38, v0
	v_mov_b32_e32 v39, v0
	v_mov_b32_e32 v40, v0
	v_mov_b32_e32 v41, v0
	v_mov_b32_e32 v42, v0
	v_mov_b32_e32 v43, v0
	v_mov_b32_e32 v44, v0
	v_mov_b32_e32 v45, v0
	v_mov_b32_e32 v46, v0
	v_mov_b32_e32 v47, v0
	v_mov_b32_e32 v48, v0
	v_mov_b32_e32 v49, v0
	v_mov_b32_e32 v50, v0
	v_mov_b32_e32 v51, v0
	v_mov_b32_e32 v52, v0
	v_mov_b32_e32 v53, v0
	v_mov_b32_e32 v54, v0
	v_mov_b32_e32 v55, v0
	v_mov_b32_e32 v56, v0
	v_mov_b32_e32 v57, v0
	v_mov_b32_e32 v62, v0
	v_mov_b32_e32 v63, v0
	v_mov_b32_e32 v64, v0
	v_mov_b32_e32 v65, v0
	v_mov_b32_e32 v70, v0
	v_mov_b32_e32 v71, v0
	v_mov_b32_e32 v72, v0
	v_mov_b32_e32 v73, v0
	v_mov_b32_e32 v98, v0
	v_mov_b32_e32 v99, v0
	v_mov_b32_e32 v100, v0
	v_mov_b32_e32 v101, v0
	v_mov_b32_e32 v102, v0
	v_mov_b32_e32 v103, v0
	v_mov_b32_e32 v104, v0
	v_mov_b32_e32 v105, v0
	v_mov_b32_e32 v106, v0
	v_mov_b32_e32 v107, v0
	v_mov_b32_e32 v108, v0
	v_mov_b32_e32 v109, v0
	v_mov_b32_e32 v110, v0
	v_mov_b32_e32 v111, v0
	v_mov_b32_e32 v112, v0
	v_mov_b32_e32 v113, v0
	v_mov_b32_e32 v114, v0
	v_mov_b32_e32 v115, v0
	v_mov_b32_e32 v116, v0
	v_mov_b32_e32 v117, v0
	v_mov_b32_e32 v118, v0
	v_mov_b32_e32 v119, v0
	v_mov_b32_e32 v120, v0
	v_mov_b32_e32 v121, v0
	v_mov_b32_e32 v130, v0
	v_mov_b32_e32 v131, v0
	v_mov_b32_e32 v132, v0
	v_mov_b32_e32 v133, v0
	v_mov_b32_e32 v134, v0
	v_mov_b32_e32 v135, v0
	v_mov_b32_e32 v136, v0
	v_mov_b32_e32 v137, v0
	s_and_b64 vcc, exec, s[20:21]
	s_cbranch_vccz .Lprio_skip_3
	s_setprio 1

.LBB0_1750:
	s_ashr_i32 s27, s26, 31
	s_lshl_b64 s[4:5], s[26:27], 20
	s_add_u32 s30, s46, s4
	s_addc_u32 s31, s47, s5
	s_and_b64 s[4:5], s[36:37], exec
	s_cselect_b32 s4, s31, s43
	s_cselect_b32 s5, s30, s42
	s_ashr_i32 s23, s22, 31
	s_lshl_b64 s[38:39], s[22:23], 20
	s_add_u32 s38, s24, s38
	s_addc_u32 s39, s48, s39
	s_and_b64 s[44:45], s[36:37], exec
	s_cselect_b32 s23, s39, s35
	s_cselect_b32 s27, s38, s34
	s_add_u32 s59, s34, 0x100
	s_addc_u32 s60, s35, 0
	s_add_u32 s42, s42, 0x80080
	v_mov_b32_e32 v0, 0
	s_addc_u32 s43, s43, 0
	s_mov_b32 s61, -2
	v_mov_b32_e32 v1, v0
	v_mov_b32_e32 v2, v0
	v_mov_b32_e32 v3, v0
	v_mov_b32_e32 v8, v0
	v_mov_b32_e32 v9, v0
	v_mov_b32_e32 v10, v0
	v_mov_b32_e32 v11, v0
	v_mov_b32_e32 v18, v0
	v_mov_b32_e32 v19, v0
	v_mov_b32_e32 v20, v0
	v_mov_b32_e32 v21, v0
	v_mov_b32_e32 v26, v0
	v_mov_b32_e32 v27, v0
	v_mov_b32_e32 v28, v0
	v_mov_b32_e32 v29, v0
	v_mov_b32_e32 v34, v0
	v_mov_b32_e32 v35, v0
	v_mov_b32_e32 v36, v0
	v_mov_b32_e32 v37, v0
	v_mov_b32_e32 v42, v0
	v_mov_b32_e32 v43, v0
	v_mov_b32_e32 v44, v0
	v_mov_b32_e32 v45, v0
	v_mov_b32_e32 v50, v0
	v_mov_b32_e32 v51, v0
	v_mov_b32_e32 v52, v0
	v_mov_b32_e32 v53, v0
	v_mov_b32_e32 v58, v0
	v_mov_b32_e32 v59, v0
	v_mov_b32_e32 v60, v0
	v_mov_b32_e32 v61, v0
	v_mov_b32_e32 v4, v0
	v_mov_b32_e32 v5, v0
	v_mov_b32_e32 v6, v0
	v_mov_b32_e32 v7, v0
	v_mov_b32_e32 v12, v0
	v_mov_b32_e32 v13, v0
	v_mov_b32_e32 v14, v0
	v_mov_b32_e32 v15, v0
	v_mov_b32_e32 v22, v0
	v_mov_b32_e32 v23, v0
	v_mov_b32_e32 v24, v0
	v_mov_b32_e32 v25, v0
	v_mov_b32_e32 v30, v0
	v_mov_b32_e32 v31, v0
	v_mov_b32_e32 v32, v0
	v_mov_b32_e32 v33, v0
	v_mov_b32_e32 v38, v0
	v_mov_b32_e32 v39, v0
	v_mov_b32_e32 v40, v0
	v_mov_b32_e32 v41, v0
	v_mov_b32_e32 v46, v0
	v_mov_b32_e32 v47, v0
	v_mov_b32_e32 v48, v0
	v_mov_b32_e32 v49, v0
	v_mov_b32_e32 v54, v0
	v_mov_b32_e32 v55, v0
	v_mov_b32_e32 v56, v0
	v_mov_b32_e32 v57, v0
	v_mov_b32_e32 v62, v0
	v_mov_b32_e32 v63, v0
	v_mov_b32_e32 v64, v0
	v_mov_b32_e32 v65, v0
	v_mov_b32_e32 v66, v0
	v_mov_b32_e32 v67, v0
	v_mov_b32_e32 v68, v0
	v_mov_b32_e32 v69, v0
	v_mov_b32_e32 v74, v0
	v_mov_b32_e32 v75, v0
	v_mov_b32_e32 v76, v0
	v_mov_b32_e32 v77, v0
	v_mov_b32_e32 v82, v0
	v_mov_b32_e32 v83, v0
	v_mov_b32_e32 v84, v0
	v_mov_b32_e32 v85, v0
	v_mov_b32_e32 v90, v0
	v_mov_b32_e32 v91, v0
	v_mov_b32_e32 v92, v0
	v_mov_b32_e32 v93, v0
	v_mov_b32_e32 v98, v0
	v_mov_b32_e32 v99, v0
	v_mov_b32_e32 v100, v0
	v_mov_b32_e32 v101, v0
	v_mov_b32_e32 v106, v0
	v_mov_b32_e32 v107, v0
	v_mov_b32_e32 v108, v0
	v_mov_b32_e32 v109, v0
	v_mov_b32_e32 v114, v0
	v_mov_b32_e32 v115, v0
	v_mov_b32_e32 v116, v0
	v_mov_b32_e32 v117, v0
	v_mov_b32_e32 v122, v0
	v_mov_b32_e32 v123, v0
	v_mov_b32_e32 v124, v0
	v_mov_b32_e32 v125, v0
	v_mov_b32_e32 v70, v0
	v_mov_b32_e32 v71, v0
	v_mov_b32_e32 v72, v0
	v_mov_b32_e32 v73, v0
	v_mov_b32_e32 v78, v0
	v_mov_b32_e32 v79, v0
	v_mov_b32_e32 v80, v0
	v_mov_b32_e32 v81, v0
	v_mov_b32_e32 v86, v0
	v_mov_b32_e32 v87, v0
	v_mov_b32_e32 v88, v0
	v_mov_b32_e32 v89, v0
	v_mov_b32_e32 v94, v0
	v_mov_b32_e32 v95, v0
	v_mov_b32_e32 v96, v0
	v_mov_b32_e32 v97, v0
	v_mov_b32_e32 v102, v0
	v_mov_b32_e32 v103, v0
	v_mov_b32_e32 v104, v0
	v_mov_b32_e32 v105, v0
	v_mov_b32_e32 v110, v0
	v_mov_b32_e32 v111, v0
	v_mov_b32_e32 v112, v0
	v_mov_b32_e32 v113, v0
	v_mov_b32_e32 v118, v0
	v_mov_b32_e32 v119, v0
	v_mov_b32_e32 v120, v0
	v_mov_b32_e32 v121, v0
	v_mov_b32_e32 v126, v0
	v_mov_b32_e32 v127, v0
	v_mov_b32_e32 v128, v0
	v_mov_b32_e32 v129, v0
	s_and_b64 vcc, exec, s[20:21]
	s_cbranch_vccz .Lprio_skip_4
	s_setprio 1

.LBB0_1829:
	s_add_u32 s4, s34, 0x100
	v_mov_b32_e32 v0, 0
	s_addc_u32 s5, s35, 0
	s_mov_b32 s61, -2
	v_mov_b32_e32 v1, v0
	v_mov_b32_e32 v2, v0
	v_mov_b32_e32 v3, v0
	v_mov_b32_e32 v4, v0
	v_mov_b32_e32 v5, v0
	v_mov_b32_e32 v6, v0
	v_mov_b32_e32 v7, v0
	v_mov_b32_e32 v8, v0
	v_mov_b32_e32 v9, v0
	v_mov_b32_e32 v10, v0
	v_mov_b32_e32 v11, v0
	v_mov_b32_e32 v12, v0
	v_mov_b32_e32 v13, v0
	v_mov_b32_e32 v14, v0
	v_mov_b32_e32 v15, v0
	v_mov_b32_e32 v18, v0
	v_mov_b32_e32 v19, v0
	v_mov_b32_e32 v20, v0
	v_mov_b32_e32 v21, v0
	v_mov_b32_e32 v22, v0
	v_mov_b32_e32 v23, v0
	v_mov_b32_e32 v24, v0
	v_mov_b32_e32 v25, v0
	v_mov_b32_e32 v26, v0
	v_mov_b32_e32 v27, v0
	v_mov_b32_e32 v28, v0
	v_mov_b32_e32 v29, v0
	v_mov_b32_e32 v30, v0
	v_mov_b32_e32 v31, v0
	v_mov_b32_e32 v32, v0
	v_mov_b32_e32 v33, v0
	v_mov_b32_e32 v66, v0
	v_mov_b32_e32 v67, v0
	v_mov_b32_e32 v68, v0
	v_mov_b32_e32 v69, v0
	v_mov_b32_e32 v70, v0
	v_mov_b32_e32 v71, v0
	v_mov_b32_e32 v72, v0
	v_mov_b32_e32 v73, v0
	v_mov_b32_e32 v74, v0
	v_mov_b32_e32 v75, v0
	v_mov_b32_e32 v76, v0
	v_mov_b32_e32 v77, v0
	v_mov_b32_e32 v78, v0
	v_mov_b32_e32 v79, v0
	v_mov_b32_e32 v80, v0
	v_mov_b32_e32 v81, v0
	v_mov_b32_e32 v82, v0
	v_mov_b32_e32 v83, v0
	v_mov_b32_e32 v84, v0
	v_mov_b32_e32 v85, v0
	v_mov_b32_e32 v86, v0
	v_mov_b32_e32 v87, v0
	v_mov_b32_e32 v88, v0
	v_mov_b32_e32 v89, v0
	v_mov_b32_e32 v90, v0
	v_mov_b32_e32 v91, v0
	v_mov_b32_e32 v92, v0
	v_mov_b32_e32 v93, v0
	v_mov_b32_e32 v94, v0
	v_mov_b32_e32 v95, v0
	v_mov_b32_e32 v96, v0
	v_mov_b32_e32 v97, v0
	v_mov_b32_e32 v34, v0
	v_mov_b32_e32 v35, v0
	v_mov_b32_e32 v36, v0
	v_mov_b32_e32 v37, v0
	v_mov_b32_e32 v38, v0
	v_mov_b32_e32 v39, v0
	v_mov_b32_e32 v40, v0
	v_mov_b32_e32 v41, v0
	v_mov_b32_e32 v42, v0
	v_mov_b32_e32 v43, v0
	v_mov_b32_e32 v44, v0
	v_mov_b32_e32 v45, v0
	v_mov_b32_e32 v46, v0
	v_mov_b32_e32 v47, v0
	v_mov_b32_e32 v48, v0
	v_mov_b32_e32 v49, v0
	v_mov_b32_e32 v50, v0
	v_mov_b32_e32 v51, v0
	v_mov_b32_e32 v52, v0
	v_mov_b32_e32 v53, v0
	v_mov_b32_e32 v54, v0
	v_mov_b32_e32 v55, v0
	v_mov_b32_e32 v56, v0
	v_mov_b32_e32 v57, v0
	v_mov_b32_e32 v58, v0
	v_mov_b32_e32 v59, v0
	v_mov_b32_e32 v60, v0
	v_mov_b32_e32 v61, v0
	v_mov_b32_e32 v62, v0
	v_mov_b32_e32 v63, v0
	v_mov_b32_e32 v64, v0
	v_mov_b32_e32 v65, v0
	v_mov_b32_e32 v98, v0
	v_mov_b32_e32 v99, v0
	v_mov_b32_e32 v100, v0
	v_mov_b32_e32 v101, v0
	v_mov_b32_e32 v102, v0
	v_mov_b32_e32 v103, v0
	v_mov_b32_e32 v104, v0
	v_mov_b32_e32 v105, v0
	v_mov_b32_e32 v106, v0
	v_mov_b32_e32 v107, v0
	v_mov_b32_e32 v108, v0
	v_mov_b32_e32 v109, v0
	v_mov_b32_e32 v110, v0
	v_mov_b32_e32 v111, v0
	v_mov_b32_e32 v112, v0
	v_mov_b32_e32 v113, v0
	v_mov_b32_e32 v114, v0
	v_mov_b32_e32 v115, v0
	v_mov_b32_e32 v116, v0
	v_mov_b32_e32 v117, v0
	v_mov_b32_e32 v118, v0
	v_mov_b32_e32 v119, v0
	v_mov_b32_e32 v120, v0
	v_mov_b32_e32 v121, v0
	v_mov_b32_e32 v122, v0
	v_mov_b32_e32 v123, v0
	v_mov_b32_e32 v124, v0
	v_mov_b32_e32 v125, v0
	v_mov_b32_e32 v126, v0
	v_mov_b32_e32 v127, v0
	v_mov_b32_e32 v128, v0
	v_mov_b32_e32 v129, v0
	s_and_b64 vcc, exec, s[20:21]
	s_cbranch_vccz .Lprio_skip_5
	s_setprio 1
